# P13: output copy loop done only by the non-chunk blocks so chunk blocks start the scan at once
# speedup vs baseline: 1.0178x; 1.0080x over previous
.LBB0_2438:
	v_readlane_b32 s0, v245, 0
	v_readlane_b32 s1, v245, 1
	v_readlane_b32 s98, v245, 9
	s_cmpk_lg_u32 s98, 0x200
	s_cbranch_scc1 .Lp13c_go
	s_cmpk_lt_u32 s0, 0x100
	s_cbranch_scc1 .LBB0_2445
	s_sub_u32 s0, s0, 0x100
	s_sub_u32 s98, s98, 0x100
.Lp13c_go:
	v_lshl_add_u32 v2, s0, 8, v1
	s_mov_b32 s0, 0x132000
	v_cmp_gt_i32_e32 vcc, s0, v2
	s_and_saveexec_b64 s[0:1], vcc
	s_cbranch_execz .LBB0_2445
	v_readlane_b32 s4, v245, 7
	s_add_u32 s2, s82, 0x10740000
	v_readlane_b32 s6, v245, 9
	s_addc_u32 s3, s83, 0
	v_readlane_b32 s5, v245, 8
	v_readlane_b32 s7, v245, 10
	s_lshl_b32 s4, s98, 8
	s_waitcnt vmcnt(10)
	v_add_u32_e32 v12, 0xfffee000, v2
	v_ashrrev_i32_e32 v3, 31, v2
	s_ashr_i32 s5, s4, 31
	s_mov_b64 s[6:7], 0
	s_mov_b32 s10, 0x12000
	s_mov_b32 s11, 0x11fff
	s_mov_b32 s12, 0x38e38e39
	s_movk_i32 s13, 0xdc00
	s_mov_b32 s14, 0x2aaaaaab
	s_movk_i32 s15, 0xf400
	s_movk_i32 s16, 0x4081
	s_movk_i32 s17, 0x1800
	v_mov_b32_e32 v5, 0
	s_movk_i32 s18, 0x80d
	s_mov_b32 s19, 0x131fff
	s_branch .LBB0_2441
